# last layer's down-GEMM epilogue: the bf16 residual copy (16 write-through stores per wave) that nothing reads after the final update is no longer stored
# baseline (speedup 1.0000x reference)
.LBB0_956:
	v_lshl_add_u32 v194, s55, 8, v228
	v_lshl_or_b32 v212, s54, 8, v230
	v_ashrrev_i32_e32 v213, 31, v212
	v_ashrrev_i32_e32 v195, 31, v194
	v_lshl_add_u64 v[122:123], v[212:213], 1, s[10:11]
	v_lshlrev_b64 v[124:125], 11, v[194:195]
	v_lshl_add_u64 v[124:125], v[122:123], 0, v[124:125]
	global_load_dwordx4 v[190:193], v[124:125], off
	global_load_dwordx4 v[186:189], v[124:125], off offset:256
	v_or_b32_e32 v226, 16, v194
	v_ashrrev_i32_e32 v227, 31, v226
	v_lshlrev_b64 v[124:125], 11, v[226:227]
	v_lshl_add_u64 v[124:125], v[122:123], 0, v[124:125]
	global_load_dwordx4 v[182:185], v[124:125], off
	global_load_dwordx4 v[178:181], v[124:125], off offset:256
	v_or_b32_e32 v224, 32, v194
	v_ashrrev_i32_e32 v225, 31, v224
	v_lshlrev_b64 v[124:125], 11, v[224:225]
	v_lshl_add_u64 v[124:125], v[122:123], 0, v[124:125]
	global_load_dwordx4 v[174:177], v[124:125], off
	global_load_dwordx4 v[170:173], v[124:125], off offset:256
	v_or_b32_e32 v222, 48, v194
	v_ashrrev_i32_e32 v223, 31, v222
	v_lshlrev_b64 v[124:125], 11, v[222:223]
	v_lshl_add_u64 v[124:125], v[122:123], 0, v[124:125]
	global_load_dwordx4 v[166:169], v[124:125], off
	global_load_dwordx4 v[162:165], v[124:125], off offset:256
	v_add_u32_e32 v220, 0x80, v194
	v_ashrrev_i32_e32 v221, 31, v220
	v_lshlrev_b64 v[124:125], 11, v[220:221]
	v_lshl_add_u64 v[124:125], v[122:123], 0, v[124:125]
	global_load_dwordx4 v[158:161], v[124:125], off
	global_load_dwordx4 v[154:157], v[124:125], off offset:256
	v_add_u32_e32 v218, 0x90, v194
	v_ashrrev_i32_e32 v219, 31, v218
	v_lshlrev_b64 v[124:125], 11, v[218:219]
	v_lshl_add_u64 v[124:125], v[122:123], 0, v[124:125]
	global_load_dwordx4 v[150:153], v[124:125], off
	global_load_dwordx4 v[146:149], v[124:125], off offset:256
	v_add_u32_e32 v216, 0xa0, v194
	v_ashrrev_i32_e32 v217, 31, v216
	v_lshlrev_b64 v[124:125], 11, v[216:217]
	v_lshl_add_u64 v[124:125], v[122:123], 0, v[124:125]
	global_load_dwordx4 v[142:145], v[124:125], off
	global_load_dwordx4 v[134:137], v[124:125], off offset:256
	v_add_u32_e32 v214, 0xb0, v194
	v_ashrrev_i32_e32 v215, 31, v214
	v_lshlrev_b64 v[124:125], 11, v[214:215]
	v_lshl_add_u64 v[122:123], v[122:123], 0, v[124:125]
	global_load_dwordx4 v[138:141], v[122:123], off
	s_nop 0
	global_load_dwordx4 v[122:125], v[122:123], off offset:256
	v_lshlrev_b64 v[194:195], 10, v[194:195]
	v_lshl_add_u64 v[194:195], v[194:195], 0, v[212:213]
	s_mov_b64 s[24:25], -1
	s_andn2_b64 vcc, exec, s[6:7]
	s_waitcnt vmcnt(0)
	v_lshlrev_b32_e32 v198, 16, v190
	v_and_b32_e32 v199, 0xffff0000, v190
	v_lshlrev_b32_e32 v190, 16, v191
	v_and_b32_e32 v191, 0xffff0000, v191
	v_pk_add_f32 v[132:133], v[132:133], v[190:191]
	v_lshlrev_b32_e32 v190, 16, v192
	v_and_b32_e32 v191, 0xffff0000, v192
	v_pk_add_f32 v[130:131], v[130:131], v[198:199]
	v_lshlrev_b32_e32 v192, 16, v193
	v_and_b32_e32 v193, 0xffff0000, v193
	v_pk_add_f32 v[126:127], v[126:127], v[190:191]
	v_lshl_add_u64 v[190:191], v[194:195], 2, s[8:9]
	v_pk_add_f32 v[128:129], v[128:129], v[192:193]
	global_store_dwordx4 v[190:191], v[130:133], off nt
	global_store_dwordx4 v[190:191], v[126:129], off offset:16 nt
	s_nop 0
	v_cvt_pk_bf16_f32 v130, v130, v131
	v_cvt_pk_bf16_f32 v131, v132, v133
	v_cvt_pk_bf16_f32 v132, v126, v127
	v_cvt_pk_bf16_f32 v133, v128, v129
	v_lshl_add_u64 v[126:127], v[194:195], 1, s[10:11]
	v_lshlrev_b32_e32 v128, 16, v186
	v_and_b32_e32 v129, 0xffff0000, v186
	v_lshlrev_b32_e32 v130, 16, v187
	v_and_b32_e32 v131, 0xffff0000, v187
	v_pk_add_f32 v[120:121], v[120:121], v[130:131]
	v_pk_add_f32 v[118:119], v[118:119], v[128:129]
	v_lshlrev_b32_e32 v128, 16, v188
	v_and_b32_e32 v129, 0xffff0000, v188
	v_lshlrev_b32_e32 v130, 16, v189
	v_and_b32_e32 v131, 0xffff0000, v189
	v_pk_add_f32 v[116:117], v[116:117], v[130:131]
	v_pk_add_f32 v[114:115], v[114:115], v[128:129]
	global_store_dwordx4 v[190:191], v[118:121], off offset:512 nt
	global_store_dwordx4 v[190:191], v[114:117], off offset:528 nt
	s_nop 0
	v_cvt_pk_bf16_f32 v118, v118, v119
	v_cvt_pk_bf16_f32 v119, v120, v121
	v_cvt_pk_bf16_f32 v120, v114, v115
	v_cvt_pk_bf16_f32 v121, v116, v117
	v_lshlrev_b64 v[114:115], 10, v[226:227]
	v_lshlrev_b32_e32 v116, 16, v182
	v_and_b32_e32 v117, 0xffff0000, v182
	v_lshl_add_u64 v[114:115], v[114:115], 0, v[212:213]
	v_lshlrev_b32_e32 v118, 16, v183
	v_and_b32_e32 v119, 0xffff0000, v183
	v_pk_add_f32 v[110:111], v[110:111], v[116:117]
	v_lshlrev_b32_e32 v116, 16, v184
	v_and_b32_e32 v117, 0xffff0000, v184
	v_pk_add_f32 v[112:113], v[112:113], v[118:119]
	v_lshlrev_b32_e32 v118, 16, v185
	v_and_b32_e32 v119, 0xffff0000, v185
	v_pk_add_f32 v[106:107], v[106:107], v[116:117]
	v_lshl_add_u64 v[116:117], v[114:115], 2, s[8:9]
	v_pk_add_f32 v[108:109], v[108:109], v[118:119]
	global_store_dwordx4 v[116:117], v[110:113], off nt
	global_store_dwordx4 v[116:117], v[106:109], off offset:16 nt
	s_nop 0
	v_cvt_pk_bf16_f32 v110, v110, v111
	v_cvt_pk_bf16_f32 v111, v112, v113
	v_cvt_pk_bf16_f32 v112, v106, v107
	v_cvt_pk_bf16_f32 v113, v108, v109
	v_lshl_add_u64 v[106:107], v[114:115], 1, s[10:11]
	v_lshlrev_b32_e32 v108, 16, v178
	v_and_b32_e32 v109, 0xffff0000, v178
	v_lshlrev_b32_e32 v110, 16, v179
	v_and_b32_e32 v111, 0xffff0000, v179
	v_pk_add_f32 v[104:105], v[104:105], v[110:111]
	v_pk_add_f32 v[102:103], v[102:103], v[108:109]
	v_lshlrev_b32_e32 v108, 16, v180
	v_and_b32_e32 v109, 0xffff0000, v180
	v_lshlrev_b32_e32 v110, 16, v181
	v_and_b32_e32 v111, 0xffff0000, v181
	v_pk_add_f32 v[100:101], v[100:101], v[110:111]
	v_pk_add_f32 v[98:99], v[98:99], v[108:109]
	global_store_dwordx4 v[116:117], v[102:105], off offset:512 nt
	global_store_dwordx4 v[116:117], v[98:101], off offset:528 nt
	s_nop 0
	v_cvt_pk_bf16_f32 v102, v102, v103
	v_cvt_pk_bf16_f32 v103, v104, v105
	v_cvt_pk_bf16_f32 v104, v98, v99
	v_cvt_pk_bf16_f32 v105, v100, v101
	v_lshlrev_b64 v[98:99], 10, v[224:225]
	v_lshlrev_b32_e32 v100, 16, v174
	v_and_b32_e32 v101, 0xffff0000, v174
	v_lshl_add_u64 v[98:99], v[98:99], 0, v[212:213]
	v_lshlrev_b32_e32 v102, 16, v175
	v_and_b32_e32 v103, 0xffff0000, v175
	v_pk_add_f32 v[94:95], v[94:95], v[100:101]
	v_lshlrev_b32_e32 v100, 16, v176
	v_and_b32_e32 v101, 0xffff0000, v176
	v_pk_add_f32 v[96:97], v[96:97], v[102:103]
	v_lshlrev_b32_e32 v102, 16, v177
	v_and_b32_e32 v103, 0xffff0000, v177
	v_pk_add_f32 v[90:91], v[90:91], v[100:101]
	v_lshl_add_u64 v[100:101], v[98:99], 2, s[8:9]
	v_pk_add_f32 v[92:93], v[92:93], v[102:103]
	global_store_dwordx4 v[100:101], v[94:97], off nt
	global_store_dwordx4 v[100:101], v[90:93], off offset:16 nt
	s_nop 0
	v_cvt_pk_bf16_f32 v94, v94, v95
	v_cvt_pk_bf16_f32 v95, v96, v97
	v_cvt_pk_bf16_f32 v96, v90, v91
	v_cvt_pk_bf16_f32 v97, v92, v93
	v_lshl_add_u64 v[90:91], v[98:99], 1, s[10:11]
	v_lshlrev_b32_e32 v92, 16, v170
	v_and_b32_e32 v93, 0xffff0000, v170
	v_lshlrev_b32_e32 v94, 16, v171
	v_and_b32_e32 v95, 0xffff0000, v171
	v_pk_add_f32 v[88:89], v[88:89], v[94:95]
	v_pk_add_f32 v[86:87], v[86:87], v[92:93]
	v_lshlrev_b32_e32 v92, 16, v172
	v_and_b32_e32 v93, 0xffff0000, v172
	v_lshlrev_b32_e32 v94, 16, v173
	v_and_b32_e32 v95, 0xffff0000, v173
	v_pk_add_f32 v[84:85], v[84:85], v[94:95]
	v_pk_add_f32 v[82:83], v[82:83], v[92:93]
	global_store_dwordx4 v[100:101], v[86:89], off offset:512 nt
	global_store_dwordx4 v[100:101], v[82:85], off offset:528 nt
	s_nop 0
	v_cvt_pk_bf16_f32 v86, v86, v87
	v_cvt_pk_bf16_f32 v87, v88, v89
	v_cvt_pk_bf16_f32 v88, v82, v83
	v_cvt_pk_bf16_f32 v89, v84, v85
	v_lshlrev_b64 v[82:83], 10, v[222:223]
	v_lshlrev_b32_e32 v84, 16, v166
	v_and_b32_e32 v85, 0xffff0000, v166
	v_lshl_add_u64 v[82:83], v[82:83], 0, v[212:213]
	v_lshlrev_b32_e32 v86, 16, v167
	v_and_b32_e32 v87, 0xffff0000, v167
	v_pk_add_f32 v[78:79], v[78:79], v[84:85]
	v_lshlrev_b32_e32 v84, 16, v168
	v_and_b32_e32 v85, 0xffff0000, v168
	v_pk_add_f32 v[80:81], v[80:81], v[86:87]
	v_lshlrev_b32_e32 v86, 16, v169
	v_and_b32_e32 v87, 0xffff0000, v169
	v_pk_add_f32 v[74:75], v[74:75], v[84:85]
	v_lshl_add_u64 v[84:85], v[82:83], 2, s[8:9]
	v_pk_add_f32 v[76:77], v[76:77], v[86:87]
	global_store_dwordx4 v[84:85], v[78:81], off nt
	global_store_dwordx4 v[84:85], v[74:77], off offset:16 nt
	s_nop 0
	v_cvt_pk_bf16_f32 v78, v78, v79
	v_cvt_pk_bf16_f32 v79, v80, v81
	v_cvt_pk_bf16_f32 v80, v74, v75
	v_cvt_pk_bf16_f32 v81, v76, v77
	v_lshl_add_u64 v[74:75], v[82:83], 1, s[10:11]
	v_lshlrev_b32_e32 v76, 16, v162
	v_and_b32_e32 v77, 0xffff0000, v162
	v_lshlrev_b32_e32 v78, 16, v163
	v_and_b32_e32 v79, 0xffff0000, v163
	v_pk_add_f32 v[72:73], v[72:73], v[78:79]
	v_pk_add_f32 v[70:71], v[70:71], v[76:77]
	v_lshlrev_b32_e32 v76, 16, v164
	v_and_b32_e32 v77, 0xffff0000, v164
	v_lshlrev_b32_e32 v78, 16, v165
	v_and_b32_e32 v79, 0xffff0000, v165
	v_pk_add_f32 v[68:69], v[68:69], v[78:79]
	v_pk_add_f32 v[66:67], v[66:67], v[76:77]
	global_store_dwordx4 v[84:85], v[70:73], off offset:512 nt
	global_store_dwordx4 v[84:85], v[66:69], off offset:528 nt
	s_nop 0
	v_cvt_pk_bf16_f32 v70, v70, v71
	v_cvt_pk_bf16_f32 v71, v72, v73
	v_cvt_pk_bf16_f32 v72, v66, v67
	v_cvt_pk_bf16_f32 v73, v68, v69
	v_lshlrev_b64 v[66:67], 10, v[220:221]
	v_lshlrev_b32_e32 v68, 16, v158
	v_and_b32_e32 v69, 0xffff0000, v158
	v_lshl_add_u64 v[66:67], v[66:67], 0, v[212:213]
	v_lshlrev_b32_e32 v70, 16, v159
	v_and_b32_e32 v71, 0xffff0000, v159
	v_pk_add_f32 v[62:63], v[62:63], v[68:69]
	v_lshlrev_b32_e32 v68, 16, v160
	v_and_b32_e32 v69, 0xffff0000, v160
	v_pk_add_f32 v[64:65], v[64:65], v[70:71]
	v_lshlrev_b32_e32 v70, 16, v161
	v_and_b32_e32 v71, 0xffff0000, v161
	v_pk_add_f32 v[58:59], v[58:59], v[68:69]
	v_lshl_add_u64 v[68:69], v[66:67], 2, s[8:9]
	v_pk_add_f32 v[60:61], v[60:61], v[70:71]
	global_store_dwordx4 v[68:69], v[62:65], off nt
	global_store_dwordx4 v[68:69], v[58:61], off offset:16 nt
	s_nop 0
	v_cvt_pk_bf16_f32 v62, v62, v63
	v_cvt_pk_bf16_f32 v63, v64, v65
	v_cvt_pk_bf16_f32 v64, v58, v59
	v_cvt_pk_bf16_f32 v65, v60, v61
	v_lshl_add_u64 v[58:59], v[66:67], 1, s[10:11]
	v_lshlrev_b32_e32 v60, 16, v154
	v_and_b32_e32 v61, 0xffff0000, v154
	v_lshlrev_b32_e32 v62, 16, v155
	v_and_b32_e32 v63, 0xffff0000, v155
	v_pk_add_f32 v[56:57], v[56:57], v[62:63]
	v_pk_add_f32 v[54:55], v[54:55], v[60:61]
	v_lshlrev_b32_e32 v60, 16, v156
	v_and_b32_e32 v61, 0xffff0000, v156
	v_lshlrev_b32_e32 v62, 16, v157
	v_and_b32_e32 v63, 0xffff0000, v157
	v_pk_add_f32 v[52:53], v[52:53], v[62:63]
	v_pk_add_f32 v[50:51], v[50:51], v[60:61]
	global_store_dwordx4 v[68:69], v[54:57], off offset:512 nt
	global_store_dwordx4 v[68:69], v[50:53], off offset:528 nt
	s_nop 0
	v_cvt_pk_bf16_f32 v54, v54, v55
	v_cvt_pk_bf16_f32 v55, v56, v57
	v_cvt_pk_bf16_f32 v56, v50, v51
	v_cvt_pk_bf16_f32 v57, v52, v53
	v_lshlrev_b64 v[50:51], 10, v[218:219]
	v_lshlrev_b32_e32 v52, 16, v150
	v_and_b32_e32 v53, 0xffff0000, v150
	v_lshl_add_u64 v[50:51], v[50:51], 0, v[212:213]
	v_lshlrev_b32_e32 v54, 16, v151
	v_and_b32_e32 v55, 0xffff0000, v151
	v_pk_add_f32 v[46:47], v[46:47], v[52:53]
	v_lshlrev_b32_e32 v52, 16, v152
	v_and_b32_e32 v53, 0xffff0000, v152
	v_pk_add_f32 v[48:49], v[48:49], v[54:55]
	v_lshlrev_b32_e32 v54, 16, v153
	v_and_b32_e32 v55, 0xffff0000, v153
	v_pk_add_f32 v[42:43], v[42:43], v[52:53]
	v_lshl_add_u64 v[52:53], v[50:51], 2, s[8:9]
	v_pk_add_f32 v[44:45], v[44:45], v[54:55]
	global_store_dwordx4 v[52:53], v[46:49], off nt
	global_store_dwordx4 v[52:53], v[42:45], off offset:16 nt
	s_nop 0
	v_cvt_pk_bf16_f32 v46, v46, v47
	v_cvt_pk_bf16_f32 v47, v48, v49
	v_cvt_pk_bf16_f32 v48, v42, v43
	v_cvt_pk_bf16_f32 v49, v44, v45
	v_lshl_add_u64 v[42:43], v[50:51], 1, s[10:11]
	v_lshlrev_b32_e32 v44, 16, v146
	v_and_b32_e32 v45, 0xffff0000, v146
	v_lshlrev_b32_e32 v46, 16, v147
	v_and_b32_e32 v47, 0xffff0000, v147
	v_pk_add_f32 v[40:41], v[40:41], v[46:47]
	v_pk_add_f32 v[38:39], v[38:39], v[44:45]
	v_lshlrev_b32_e32 v44, 16, v148
	v_and_b32_e32 v45, 0xffff0000, v148
	v_lshlrev_b32_e32 v46, 16, v149
	v_and_b32_e32 v47, 0xffff0000, v149
	v_pk_add_f32 v[36:37], v[36:37], v[46:47]
	v_pk_add_f32 v[34:35], v[34:35], v[44:45]
	global_store_dwordx4 v[52:53], v[38:41], off offset:512 nt
	global_store_dwordx4 v[52:53], v[34:37], off offset:528 nt
	s_nop 0
	v_cvt_pk_bf16_f32 v38, v38, v39
	v_cvt_pk_bf16_f32 v39, v40, v41
	v_cvt_pk_bf16_f32 v40, v34, v35
	v_cvt_pk_bf16_f32 v41, v36, v37
	v_lshlrev_b64 v[34:35], 10, v[216:217]
	v_lshlrev_b32_e32 v36, 16, v142
	v_and_b32_e32 v37, 0xffff0000, v142
	v_lshl_add_u64 v[34:35], v[34:35], 0, v[212:213]
	v_lshlrev_b32_e32 v38, 16, v143
	v_and_b32_e32 v39, 0xffff0000, v143
	v_pk_add_f32 v[30:31], v[30:31], v[36:37]
	v_lshlrev_b32_e32 v36, 16, v144
	v_and_b32_e32 v37, 0xffff0000, v144
	v_pk_add_f32 v[32:33], v[32:33], v[38:39]
	v_lshlrev_b32_e32 v38, 16, v145
	v_and_b32_e32 v39, 0xffff0000, v145
	v_pk_add_f32 v[26:27], v[26:27], v[36:37]
	v_lshl_add_u64 v[36:37], v[34:35], 2, s[8:9]
	v_pk_add_f32 v[28:29], v[28:29], v[38:39]
	global_store_dwordx4 v[36:37], v[30:33], off nt
	global_store_dwordx4 v[36:37], v[26:29], off offset:16 nt
	s_nop 0
	v_cvt_pk_bf16_f32 v30, v30, v31
	v_cvt_pk_bf16_f32 v31, v32, v33
	v_cvt_pk_bf16_f32 v32, v26, v27
	v_cvt_pk_bf16_f32 v33, v28, v29
	v_lshl_add_u64 v[26:27], v[34:35], 1, s[10:11]
	v_lshlrev_b32_e32 v28, 16, v134
	v_and_b32_e32 v29, 0xffff0000, v134
	v_lshlrev_b32_e32 v30, 16, v135
	v_and_b32_e32 v31, 0xffff0000, v135
	v_pk_add_f32 v[24:25], v[24:25], v[30:31]
	v_pk_add_f32 v[22:23], v[22:23], v[28:29]
	v_lshlrev_b32_e32 v28, 16, v136
	v_and_b32_e32 v29, 0xffff0000, v136
	v_lshlrev_b32_e32 v30, 16, v137
	v_and_b32_e32 v31, 0xffff0000, v137
	v_pk_add_f32 v[20:21], v[20:21], v[30:31]
	v_pk_add_f32 v[18:19], v[18:19], v[28:29]
	global_store_dwordx4 v[36:37], v[22:25], off offset:512 nt
	global_store_dwordx4 v[36:37], v[18:21], off offset:528 nt
	s_nop 0
	v_cvt_pk_bf16_f32 v22, v22, v23
	v_cvt_pk_bf16_f32 v23, v24, v25
	v_cvt_pk_bf16_f32 v24, v18, v19
	v_cvt_pk_bf16_f32 v25, v20, v21
	v_lshlrev_b64 v[18:19], 10, v[214:215]
	v_lshlrev_b32_e32 v20, 16, v138
	v_and_b32_e32 v21, 0xffff0000, v138
	v_lshl_add_u64 v[18:19], v[18:19], 0, v[212:213]
	v_lshlrev_b32_e32 v22, 16, v139
	v_and_b32_e32 v23, 0xffff0000, v139
	v_pk_add_f32 v[14:15], v[14:15], v[20:21]
	v_lshlrev_b32_e32 v20, 16, v140
	v_and_b32_e32 v21, 0xffff0000, v140
	v_pk_add_f32 v[16:17], v[16:17], v[22:23]
	v_lshlrev_b32_e32 v22, 16, v141
	v_and_b32_e32 v23, 0xffff0000, v141
	v_pk_add_f32 v[10:11], v[10:11], v[20:21]
	v_lshl_add_u64 v[20:21], v[18:19], 2, s[8:9]
	v_pk_add_f32 v[12:13], v[12:13], v[22:23]
	global_store_dwordx4 v[20:21], v[14:17], off nt
	global_store_dwordx4 v[20:21], v[10:13], off offset:16 nt
	s_nop 0
	v_cvt_pk_bf16_f32 v14, v14, v15
	v_cvt_pk_bf16_f32 v15, v16, v17
	v_cvt_pk_bf16_f32 v16, v10, v11
	v_cvt_pk_bf16_f32 v17, v12, v13
	v_lshl_add_u64 v[10:11], v[18:19], 1, s[10:11]
	v_lshlrev_b32_e32 v12, 16, v122
	v_and_b32_e32 v13, 0xffff0000, v122
	v_lshlrev_b32_e32 v14, 16, v123
	v_and_b32_e32 v15, 0xffff0000, v123
	v_pk_add_f32 v[8:9], v[8:9], v[14:15]
	v_pk_add_f32 v[6:7], v[6:7], v[12:13]
	v_lshlrev_b32_e32 v12, 16, v124
	v_and_b32_e32 v13, 0xffff0000, v124
	v_lshlrev_b32_e32 v14, 16, v125
	v_and_b32_e32 v15, 0xffff0000, v125
	v_pk_add_f32 v[4:5], v[4:5], v[14:15]
	v_pk_add_f32 v[2:3], v[2:3], v[12:13]
	global_store_dwordx4 v[20:21], v[6:9], off offset:512 nt
	global_store_dwordx4 v[20:21], v[2:5], off offset:528 nt
	s_nop 0
	v_cvt_pk_bf16_f32 v6, v6, v7
	v_cvt_pk_bf16_f32 v7, v8, v9
	v_cvt_pk_bf16_f32 v8, v2, v3
	v_cvt_pk_bf16_f32 v9, v4, v5
	s_cbranch_vccnz .LBB0_945
	s_andn2_b64 vcc, exec, s[12:13]
	s_cbranch_vccnz .LBB0_944
	s_barrier
	s_branch .LBB0_944
